# attention V tile: lane-to-row permutation removes the 2-way LDS bank conflict of the V-tile stores
# speedup vs baseline: 1.0007x; 1.0004x over previous
.LBB0_1129:
	v_add_co_u32_e32 v20, vcc, s21, v16
	s_not_b32 s63, s14
	s_nop 0
	v_addc_co_u32_e32 v21, vcc, 0, v17, vcc
	v_add_co_u32_e32 v24, vcc, s22, v16
	v_readlane_b32 s10, v254, 49
	s_nop 0
	v_addc_co_u32_e32 v25, vcc, 0, v17, vcc
	v_add_co_u32_e32 v28, vcc, s23, v16
	global_load_dwordx4 v[20:23], v[20:21], off
	s_nop 0
	global_load_dwordx4 v[24:27], v[24:25], off
	v_addc_co_u32_e32 v29, vcc, 0, v17, vcc
	v_add_co_u32_e32 v32, vcc, s24, v16
	s_movk_i32 s14, 0xf0
	s_nop 0
	v_addc_co_u32_e32 v33, vcc, 0, v17, vcc
	v_add_co_u32_e32 v36, vcc, s15, v16
	global_load_dwordx4 v[28:31], v[28:29], off
	s_nop 0
	global_load_dwordx4 v[32:35], v[32:33], off
	v_addc_co_u32_e32 v37, vcc, 0, v17, vcc
	v_add_co_u32_e32 v40, vcc, s18, v16
	v_readlane_b32 s11, v254, 50
	s_nop 0
	v_addc_co_u32_e32 v41, vcc, 0, v17, vcc
	v_add_co_u32_e32 v44, vcc, s19, v16
	global_load_dwordx4 v[36:39], v[36:37], off
	s_nop 0
	global_load_dwordx4 v[40:43], v[40:41], off
	v_addc_co_u32_e32 v45, vcc, 0, v17, vcc
	v_add_co_u32_e32 v16, vcc, s20, v16
	s_and_b64 s[10:11], s[10:11], exec
	s_nop 0
	v_addc_co_u32_e32 v17, vcc, 0, v17, vcc
	global_load_dwordx4 v[44:47], v[44:45], off
	s_nop 0
	global_load_dwordx4 v[48:51], v[16:17], off
	v_xor_b32_e32 v16, v128, v19
	v_lshlrev_b32_e32 v17, 8, v128
	v_lshlrev_b32_e32 v54, 4, v16
	v_and_or_b32 v17, v54, s14, v17
	s_load_dwordx2 s[14:15], s[8:9], 0x70
	s_cselect_b32 s10, 0, 8
	s_lshl_b32 s11, 1, s40
	s_add_u32 s20, s4, s13
	s_addc_u32 s21, s5, 0
	s_waitcnt lgkmcnt(0)
	s_add_u32 s22, s14, 0x1100000
	v_cvt_f32_u32_e32 v152, s11
	s_addc_u32 s23, s15, 0
	s_lshl_b32 s11, s12, 4
	v_and_b32_e32 v149, 63, v19
	s_or_b32 s11, s11, 1
	s_cmp_gt_i32 s28, 0
	v_cmp_gt_u32_e64 s[42:43], 32, v149
	s_cselect_b64 s[24:25], -1, 0
	s_add_i32 s18, s40, 13
	s_and_b64 s[26:27], s[0:1], s[42:43]
	s_cmp_gt_i32 s28, 1
	s_cselect_b64 s[28:29], -1, 0
	s_add_i32 s0, s40, 12
	s_lshl_b64 s[60:61], 1, s0
	v_writelane_b32 v254, s60, 52
	v_bfe_u32 v53, v19, 5, 1
	v_and_b32_e32 v150, 31, v19
	v_writelane_b32 v254, s61, 53
	s_lshl_b64 s[60:61], 2, s0
	v_writelane_b32 v254, s60, 54
	v_ashrrev_i32_e32 v130, 2, v19
	v_and_b32_e32 v178, 1, v130
	v_bfe_u32 v179, v130, 1, 2
	v_lshlrev_b32_e32 v178, 2, v178
	v_and_b32_e32 v130, -8, v130
	v_or3_b32 v130, v130, v178, v179
	v_lshlrev_b32_e32 v19, 4, v19
	v_lshlrev_b32_e32 v138, 4, v53
	v_writelane_b32 v254, s61, 55
	s_lshl_b64 s[60:61], 3, s0
	v_and_b32_e32 v16, 48, v19
	v_add_u32_e32 v151, 0, v17
	v_lshl_add_u64 v[132:133], s[6:7], 0, v[138:139]
	v_readlane_b32 s6, v253, 56
	v_mov_b32_e32 v17, v139
	v_writelane_b32 v254, s60, 56
	s_waitcnt vmcnt(8)
	ds_write_b128 v151, v[0:3]
	ds_write_b128 v151, v[8:11] offset:8192
	ds_write_b128 v151, v[4:7] offset:16384
	ds_write_b128 v151, v[12:15] offset:24576
	v_or_b32_e32 v2, s6, v150
	v_lshl_add_u64 v[0:1], s[14:15], 0, v[16:17]
	s_mov_b64 s[6:7], 0xc000000
	v_readlane_b32 s1, v253, 51
	v_writelane_b32 v254, s61, 57
	s_lshl_b64 s[60:61], 4, s0
	v_lshl_add_u64 v[134:135], v[0:1], 0, s[6:7]
	v_mov_b32_e32 v0, s1
	s_movk_i32 s1, 0x210
	v_writelane_b32 v254, s60, 58
	v_lshlrev_b32_e32 v52, 3, v18
	v_mad_u32_u24 v4, v150, s1, v0
	v_readlane_b32 s1, v253, 47
	v_writelane_b32 v254, s61, 59
	s_lshl_b64 s[60:61], 5, s0
	s_movk_i32 s50, 0x310
	v_lshl_add_u32 v160, v150, 2, s1
	v_lshlrev_b32_e32 v0, 1, v52
	v_mov_b32_e32 v1, v139
	v_readlane_b32 s1, v253, 53
	v_writelane_b32 v254, s60, 60
	v_mul_lo_u32 v55, v130, s50
	v_lshl_add_u64 v[136:137], s[4:5], 0, v[0:1]
	v_lshl_add_u32 v0, v2, 8, 0
	v_xor_b32_e32 v1, v53, v18
	v_bitop3_b32 v2, v53, v18, 2 bitop3:0x36
	v_bitop3_b32 v5, v53, v18, 4 bitop3:0x36
	v_bitop3_b32 v6, v53, v18, 6 bitop3:0x36
	v_bitop3_b32 v7, v53, v18, 8 bitop3:0x36
	v_bitop3_b32 v8, v53, v18, 10 bitop3:0x36
	v_bitop3_b32 v9, v53, v18, 12 bitop3:0x36
	v_bitop3_b32 v10, v53, v18, 14 bitop3:0x36
	v_add_u32_e32 v12, s1, v138
	v_writelane_b32 v254, s61, 61
	s_lshl_b64 s[60:61], 6, s0
	s_lshl_b64 s[0:1], 7, s0
	v_or_b32_e32 v19, 0x80, v150
	v_lshlrev_b32_e32 v157, 2, v53
	v_add_u32_e32 v3, 0, v55
	v_lshlrev_b32_e32 v1, 4, v1
	v_lshlrev_b32_e32 v2, 4, v2
	v_lshlrev_b32_e32 v5, 4, v5
	v_lshlrev_b32_e32 v6, 4, v6
	v_lshlrev_b32_e32 v7, 4, v7
	v_lshlrev_b32_e32 v8, 4, v8
	v_lshlrev_b32_e32 v9, 4, v9
	v_lshlrev_b32_e32 v10, 4, v10
	s_lshl_b64 s[4:5], 32, s53
	s_lshl_b64 s[12:13], 64, s53
	s_lshl_b64 s[14:15], 0x60, s53
	s_lshl_b64 s[44:45], 0x80, s53
	s_lshl_b64 s[46:47], 0xa0, s53
	s_lshl_b64 s[48:49], 0xc0, s53
	s_lshl_b64 s[72:73], 0xe0, s53
	s_lshl_b64 s[74:75], 0x100, s53
	s_lshl_b64 s[76:77], 0x120, s53
	s_lshl_b64 s[78:79], 0x140, s53
	s_lshl_b64 s[80:81], 0x160, s53
	v_mul_u32_u24_e32 v11, 0x310, v150
	v_mad_u32_u24 v13, v150, s50, v174
	v_writelane_b32 v254, s60, 62
	v_writelane_b32 v255, s0, 0
	s_mov_b32 s51, 0x16000
	v_add_u32_e32 v153, 0x10000, v151
	v_add_u32_e32 v154, 0x12000, v151
	v_add_u32_e32 v155, 0x14000, v151
	v_add_u32_e32 v156, 0x16000, v151
	v_sub_u32_e32 v158, v19, v157
	v_cvt_f32_ubyte0_e32 v159, v157
	v_ashrrev_i32_e32 v131, 31, v130
	s_lshl_b64 s[30:31], 1, s18
	s_lshl_b64 s[54:55], 2, s18
	s_lshl_b64 s[34:35], 3, s18
	s_lshl_b64 s[36:37], 4, s18
	s_lshl_b64 s[38:39], 5, s18
	s_lshl_b64 s[6:7], 6, s18
	s_lshl_b64 s[18:19], 7, s18
	v_writelane_b32 v254, s61, 63
	v_writelane_b32 v255, s1, 1
	s_lshl_b64 s[0:1], 0x2000, s40
	s_lshl_b32 s60, s4, 1
	s_lshl_b32 s64, s12, 1
	s_lshl_b32 s66, s14, 1
	s_lshl_b32 s56, s44, 1
	s_lshl_b32 s68, s46, 1
	s_lshl_b32 s70, s48, 1
	s_lshl_b32 s72, s72, 1
	s_lshl_b32 s74, s74, 1
	s_lshl_b32 s76, s76, 1
	s_lshl_b32 s78, s78, 1
	s_lshl_b32 s80, s80, 1
	v_add_u32_e32 v161, v3, v16
	v_add_u32_e32 v162, v4, v138
	v_add_u32_e32 v163, v0, v1
	v_add_u32_e32 v164, v0, v2
	v_add_u32_e32 v165, v0, v5
	v_add_u32_e32 v166, v0, v6
	v_add_u32_e32 v167, v0, v7
	v_add_u32_e32 v168, v0, v8
	v_add_u32_e32 v169, v0, v9
	v_add_u32_e32 v170, v0, v10
	v_add_u32_e32 v171, v12, v11
	v_add_u32_e32 v191, v12, v13
	s_lshl_b64 s[82:83], 0x4000, s40
	s_lshl_b64 s[84:85], 0x6000, s40
	s_lshl_b64 s[86:87], 0x8000, s40
	s_lshl_b64 s[88:89], 0xa000, s40
	s_lshl_b64 s[90:91], 0xc000, s40
	s_lshl_b64 s[92:93], 0xe000, s40
	s_waitcnt vmcnt(7)
	ds_write_b128 v151, v[20:23] offset:32768
	s_waitcnt vmcnt(6)
	ds_write_b128 v151, v[24:27] offset:40960
	s_waitcnt vmcnt(5)
	ds_write_b128 v151, v[28:31] offset:49152
	s_waitcnt vmcnt(4)
	ds_write_b128 v151, v[32:35] offset:57344
	s_waitcnt vmcnt(3)
	ds_write_b128 v153, v[36:39]
	s_waitcnt vmcnt(2)
	ds_write_b128 v154, v[40:43]
	s_waitcnt vmcnt(1)
	ds_write_b128 v155, v[44:47]
	s_waitcnt vmcnt(0)
	ds_write_b128 v156, v[48:51]
	s_branch .LBB0_1131
